# fused epilogue: adaLN gate/gpost and shift/scale/gpre vector loads batched up front instead of four to eight serialized round trips
# baseline (speedup 1.0000x reference)
; __device__ __forceinline__ float f16lo(unsigned w) { return (float)__builtin_bit_cast(f16x2, w)[0]; }
; __device__ __forceinline__ float f16hi(unsigned w) { return (float)__builtin_bit_cast(f16x2, w)[1]; }
;     __device__ __forceinline__ void fused(f32x4 (&acc)[2][2][4][2], const Unit& u, int wr, int wc, int fr, int fq, PG8_LAS unsigned char* lds, int wid, int lane) const {
;     ...
;         for (int bj = 0; bj < 2; ++bj)
; #pragma unroll
;             for (int n = 0; n < 2; ++n) {
;                 const int c = col0 + bj * HALF + n * 4;
;                 const f32x4 gg = *(const f32x4*)(gate + (size_t)b * 9216 + c) * *(const f32x4*)(gpost + c) * res_w;
; #pragma unroll
;                 for (int ai = 0; ai < 2; ++ai)
; #pragma unroll
;                     for (int m = 0; m < 4; ++m) { const int r = ai * HALF + wr * 64 + m * 16 + fr;
;                         const unsigned w0 = n ? pre[ai][m][bj].z : pre[ai][m][bj].x, w1 = n ? pre[ai][m][bj].w : pre[ai][m][bj].y;
;                         const f32x4 xv = {f16lo(w0), f16hi(w0), f16lo(w1), f16hi(w1)};
;                         acc[ai][bj][m][n] = xv + gg * (acc[ai][bj][m][n] * S[r]); }
.LBB0_753:
	s_or_b64 exec, exec, s[34:35]
	s_ashr_i32 s8, s39, 31
	s_lshr_b32 s8, s8, 27
	s_add_i32 s8, s39, s8
	s_ashr_i32 s8, s8, 5
	s_mul_i32 s35, s8, 0x9000
	s_mul_hi_i32 s34, s8, 0x9000
	s_add_u32 s8, s30, s35
	s_addc_u32 s9, s31, s34
	s_waitcnt lgkmcnt(0)
	v_lshlrev_b64 v[208:209], 2, v[0:1]
	s_waitcnt lgkmcnt(0)
	s_barrier
	v_lshl_add_u64 v[210:211], s[8:9], 0, v[208:209]
	v_lshl_add_u64 v[212:213], s[28:29], 0, v[208:209]
	flat_load_dwordx4 v[214:217], v[210:211]
	flat_load_dwordx4 v[236:239], v[212:213]
	flat_load_dwordx4 v[244:247], v[210:211] offset:16
	flat_load_dwordx4 v[248:251], v[212:213] offset:16
	flat_load_dwordx4 v[196:199], v[210:211] offset:512
	flat_load_dwordx4 v[200:203], v[212:213] offset:512
	s_and_b32 s11, s17, 0xffffff00
	s_add_i32 s11, s11, 0
	v_lshl_add_u32 v227, v219, 2, s11
	s_cmp_lg_u64 s[12:13], 0
	s_cselect_b64 s[8:9], -1, 0
	s_cmp_eq_u64 s[12:13], 0
	s_waitcnt vmcnt(4) lgkmcnt(0)
	v_pk_mul_f32 v[216:217], v[216:217], v[238:239]
	v_pk_mul_f32 v[236:237], v[214:215], v[236:237]
	v_pk_mul_f32 v[214:215], s[16:17], v[216:217] op_sel_hi:[0,1]
	v_pk_mul_f32 v[216:217], s[16:17], v[236:237] op_sel_hi:[0,1]
	v_cvt_f32_f16_sdwa v237, v192 dst_sel:DWORD dst_unused:UNUSED_PAD src0_sel:WORD_1
	v_cvt_f32_f16_e32 v236, v192
	v_add_u32_e32 v192, 0x1000, v227
	ds_read2_b32 v[240:241], v192 offset1:16
	v_cvt_f32_f16_sdwa v239, v193 dst_sel:DWORD dst_unused:UNUSED_PAD src0_sel:WORD_1
	v_cvt_f32_f16_e32 v238, v193
	s_waitcnt lgkmcnt(0)
	v_pk_mul_f32 v[96:97], v[96:97], v[240:241] op_sel_hi:[1,0]
	s_nop 0
	v_pk_fma_f32 v[96:97], v[216:217], v[96:97], v[236:237]
	v_cvt_f32_f16_sdwa v237, v188 dst_sel:DWORD dst_unused:UNUSED_PAD src0_sel:WORD_1
	v_cvt_f32_f16_e32 v236, v188
	v_mov_b32_e32 v188, v241
	v_pk_mul_f32 v[98:99], v[98:99], v[240:241] op_sel_hi:[1,0]
	v_pk_mul_f32 v[88:89], v[88:89], v[188:189] op_sel_hi:[1,0]
	v_pk_fma_f32 v[98:99], v[214:215], v[98:99], v[238:239]
	v_cvt_f32_f16_sdwa v239, v189 dst_sel:DWORD dst_unused:UNUSED_PAD src0_sel:WORD_1
	v_cvt_f32_f16_e32 v238, v189
	v_pk_mul_f32 v[90:91], v[90:91], v[188:189] op_sel_hi:[1,0]
	v_pk_fma_f32 v[88:89], v[216:217], v[88:89], v[236:237]
	v_cvt_f32_f16_sdwa v189, v184 dst_sel:DWORD dst_unused:UNUSED_PAD src0_sel:WORD_1
	v_cvt_f32_f16_e32 v188, v184
	v_cvt_f32_f16_sdwa v237, v185 dst_sel:DWORD dst_unused:UNUSED_PAD src0_sel:WORD_1
	v_cvt_f32_f16_e32 v236, v185
	ds_read2_b32 v[184:185], v192 offset0:32 offset1:48
	v_pk_fma_f32 v[90:91], v[214:215], v[90:91], v[238:239]
	s_waitcnt lgkmcnt(0)
	v_pk_mul_f32 v[92:93], v[92:93], v[184:185] op_sel_hi:[1,0]
	v_pk_mul_f32 v[94:95], v[94:95], v[184:185] op_sel_hi:[1,0]
	v_pk_fma_f32 v[92:93], v[216:217], v[92:93], v[188:189]
	v_cvt_f32_f16_sdwa v189, v180 dst_sel:DWORD dst_unused:UNUSED_PAD src0_sel:WORD_1
	v_cvt_f32_f16_e32 v188, v180
	v_mov_b32_e32 v180, v185
	v_pk_fma_f32 v[94:95], v[214:215], v[94:95], v[236:237]
	v_cvt_f32_f16_sdwa v237, v181 dst_sel:DWORD dst_unused:UNUSED_PAD src0_sel:WORD_1
	v_cvt_f32_f16_e32 v236, v181
	v_pk_mul_f32 v[74:75], v[74:75], v[180:181] op_sel_hi:[1,0]
	v_pk_mul_f32 v[72:73], v[72:73], v[180:181] op_sel_hi:[1,0]
	v_cvt_f32_f16_sdwa v181, v176 dst_sel:DWORD dst_unused:UNUSED_PAD src0_sel:WORD_1
	v_cvt_f32_f16_e32 v180, v176
	v_cvt_f32_f16_sdwa v185, v177 dst_sel:DWORD dst_unused:UNUSED_PAD src0_sel:WORD_1
	v_cvt_f32_f16_e32 v184, v177
	ds_read2_b32 v[176:177], v192 offset0:128 offset1:144
	v_pk_fma_f32 v[74:75], v[214:215], v[74:75], v[236:237]
	v_pk_fma_f32 v[72:73], v[216:217], v[72:73], v[188:189]
	s_waitcnt lgkmcnt(0)
	v_pk_mul_f32 v[80:81], v[80:81], v[176:177] op_sel_hi:[1,0]
	v_pk_mul_f32 v[82:83], v[82:83], v[176:177] op_sel_hi:[1,0]
	v_pk_fma_f32 v[80:81], v[216:217], v[80:81], v[180:181]
	v_cvt_f32_f16_sdwa v181, v172 dst_sel:DWORD dst_unused:UNUSED_PAD src0_sel:WORD_1
	v_cvt_f32_f16_e32 v180, v172
	v_mov_b32_e32 v172, v177
	v_pk_fma_f32 v[82:83], v[214:215], v[82:83], v[184:185]
	v_cvt_f32_f16_sdwa v185, v173 dst_sel:DWORD dst_unused:UNUSED_PAD src0_sel:WORD_1
	v_cvt_f32_f16_e32 v184, v173
	v_pk_mul_f32 v[66:67], v[66:67], v[172:173] op_sel_hi:[1,0]
	v_pk_mul_f32 v[64:65], v[64:65], v[172:173] op_sel_hi:[1,0]
	v_cvt_f32_f16_sdwa v173, v168 dst_sel:DWORD dst_unused:UNUSED_PAD src0_sel:WORD_1
	v_cvt_f32_f16_e32 v172, v168
	v_cvt_f32_f16_sdwa v177, v169 dst_sel:DWORD dst_unused:UNUSED_PAD src0_sel:WORD_1
	v_cvt_f32_f16_e32 v176, v169
	ds_read2_b32 v[168:169], v192 offset0:160 offset1:176
	v_pk_fma_f32 v[66:67], v[214:215], v[66:67], v[184:185]
	v_pk_fma_f32 v[64:65], v[216:217], v[64:65], v[180:181]
	s_waitcnt lgkmcnt(0)
	v_pk_mul_f32 v[70:71], v[70:71], v[168:169] op_sel_hi:[1,0]
	v_pk_mul_f32 v[68:69], v[68:69], v[168:169] op_sel_hi:[1,0]
	v_pk_fma_f32 v[70:71], v[214:215], v[70:71], v[176:177]
	v_pk_fma_f32 v[68:69], v[216:217], v[68:69], v[172:173]
	v_cvt_f32_f16_sdwa v173, v164 dst_sel:DWORD dst_unused:UNUSED_PAD src0_sel:WORD_1
	v_cvt_f32_f16_e32 v172, v164
	v_cvt_f32_f16_sdwa v177, v165 dst_sel:DWORD dst_unused:UNUSED_PAD src0_sel:WORD_1
	v_cvt_f32_f16_e32 v176, v165
	v_mov_b32_e32 v164, v169
	v_pk_mul_f32 v[54:55], v[54:55], v[164:165] op_sel_hi:[1,0]
	v_pk_mul_f32 v[52:53], v[52:53], v[164:165] op_sel_hi:[1,0]
	v_pk_fma_f32 v[54:55], v[214:215], v[54:55], v[176:177]
	v_pk_fma_f32 v[52:53], v[216:217], v[52:53], v[172:173]
	flat_load_dwordx4 v[214:217], v[210:211] offset:528
	flat_load_dwordx4 v[236:239], v[212:213] offset:528
	ds_read2_b32 v[180:181], v192 offset1:16
	v_cvt_f32_f16_sdwa v173, v194 dst_sel:DWORD dst_unused:UNUSED_PAD src0_sel:WORD_1
	v_cvt_f32_f16_e32 v172, v194
	v_cvt_f32_f16_sdwa v177, v195 dst_sel:DWORD dst_unused:UNUSED_PAD src0_sel:WORD_1
	v_cvt_f32_f16_e32 v176, v195
	s_waitcnt lgkmcnt(0)
; __device__ __forceinline__ float f16lo(unsigned w) { return (float)__builtin_bit_cast(f16x2, w)[0]; }
; __device__ __forceinline__ float f16hi(unsigned w) { return (float)__builtin_bit_cast(f16x2, w)[1]; }
;     __device__ __forceinline__ void fused(f32x4 (&acc)[2][2][4][2], const Unit& u, int wr, int wc, int fr, int fq, PG8_LAS unsigned char* lds, int wid, int lane) const {
;     ...
;         for (int bj = 0; bj < 2; ++bj)
; #pragma unroll
;             for (int n = 0; n < 2; ++n) {
;                 const int c = col0 + bj * HALF + n * 4;
;                 const f32x4 gg = *(const f32x4*)(gate + (size_t)b * 9216 + c) * *(const f32x4*)(gpost + c) * res_w;
; #pragma unroll
;                 for (int ai = 0; ai < 2; ++ai)
; #pragma unroll
;                     for (int m = 0; m < 4; ++m) { const int r = ai * HALF + wr * 64 + m * 16 + fr;
;                         const unsigned w0 = n ? pre[ai][m][bj].z : pre[ai][m][bj].x, w1 = n ? pre[ai][m][bj].w : pre[ai][m][bj].y;
;                         const f32x4 xv = {f16lo(w0), f16hi(w0), f16lo(w1), f16hi(w1)};
;                         acc[ai][bj][m][n] = xv + gg * (acc[ai][bj][m][n] * S[r]); }
;                 asm volatile("" ::: "memory");
;             }
	v_pk_mul_f32 v[162:163], v[162:163], v[180:181] op_sel_hi:[1,0]
	v_pk_mul_f32 v[160:161], v[160:161], v[180:181] op_sel_hi:[1,0]
	v_mov_b32_e32 v180, v181
	v_pk_mul_f32 v[158:159], v[158:159], v[180:181] op_sel_hi:[1,0]
	v_pk_mul_f32 v[156:157], v[156:157], v[180:181] op_sel_hi:[1,0]
	ds_read2_b32 v[180:181], v192 offset0:32 offset1:48
	s_waitcnt lgkmcnt(0)
	v_pk_mul_f32 v[154:155], v[154:155], v[180:181] op_sel_hi:[1,0]
	v_pk_mul_f32 v[152:153], v[152:153], v[180:181] op_sel_hi:[1,0]
	v_mov_b32_e32 v180, v181
	v_pk_mul_f32 v[150:151], v[150:151], v[180:181] op_sel_hi:[1,0]
	v_pk_mul_f32 v[148:149], v[148:149], v[180:181] op_sel_hi:[1,0]
	s_waitcnt vmcnt(2)
	v_pk_mul_f32 v[164:165], v[246:247], v[250:251]
	v_pk_mul_f32 v[168:169], v[244:245], v[248:249]
	v_pk_mul_f32 v[164:165], s[16:17], v[164:165] op_sel_hi:[0,1]
	v_pk_mul_f32 v[168:169], s[16:17], v[168:169] op_sel_hi:[0,1]
	v_pk_fma_f32 v[162:163], v[164:165], v[162:163], v[176:177]
	v_pk_fma_f32 v[160:161], v[168:169], v[160:161], v[172:173]
	v_cvt_f32_f16_sdwa v173, v190 dst_sel:DWORD dst_unused:UNUSED_PAD src0_sel:WORD_1
	v_cvt_f32_f16_e32 v172, v190
	v_cvt_f32_f16_sdwa v177, v191 dst_sel:DWORD dst_unused:UNUSED_PAD src0_sel:WORD_1
	v_cvt_f32_f16_e32 v176, v191
	v_pk_fma_f32 v[156:157], v[168:169], v[156:157], v[172:173]
	v_cvt_f32_f16_sdwa v173, v186 dst_sel:DWORD dst_unused:UNUSED_PAD src0_sel:WORD_1
	v_pk_fma_f32 v[158:159], v[164:165], v[158:159], v[176:177]
	v_cvt_f32_f16_e32 v172, v186
	v_cvt_f32_f16_sdwa v177, v187 dst_sel:DWORD dst_unused:UNUSED_PAD src0_sel:WORD_1
	v_cvt_f32_f16_e32 v176, v187
	v_pk_fma_f32 v[152:153], v[168:169], v[152:153], v[172:173]
	v_cvt_f32_f16_sdwa v173, v182 dst_sel:DWORD dst_unused:UNUSED_PAD src0_sel:WORD_1
	v_pk_fma_f32 v[154:155], v[164:165], v[154:155], v[176:177]
	v_cvt_f32_f16_e32 v172, v182
	v_cvt_f32_f16_sdwa v177, v183 dst_sel:DWORD dst_unused:UNUSED_PAD src0_sel:WORD_1
	v_cvt_f32_f16_e32 v176, v183
	v_pk_fma_f32 v[148:149], v[168:169], v[148:149], v[172:173]
	v_cvt_f32_f16_sdwa v173, v178 dst_sel:DWORD dst_unused:UNUSED_PAD src0_sel:WORD_1
	v_pk_fma_f32 v[150:151], v[164:165], v[150:151], v[176:177]
	v_cvt_f32_f16_e32 v172, v178
	v_cvt_f32_f16_sdwa v177, v179 dst_sel:DWORD dst_unused:UNUSED_PAD src0_sel:WORD_1
	v_cvt_f32_f16_e32 v176, v179
	ds_read2_b32 v[178:179], v192 offset0:128 offset1:144
	s_waitcnt lgkmcnt(0)
	v_pk_mul_f32 v[144:145], v[144:145], v[178:179] op_sel_hi:[1,0]
	s_nop 0
	v_pk_fma_f32 v[144:145], v[168:169], v[144:145], v[172:173]
	v_cvt_f32_f16_sdwa v173, v174 dst_sel:DWORD dst_unused:UNUSED_PAD src0_sel:WORD_1
	v_cvt_f32_f16_e32 v172, v174
	v_mov_b32_e32 v174, v179
	v_pk_mul_f32 v[146:147], v[146:147], v[178:179] op_sel_hi:[1,0]
	v_pk_mul_f32 v[136:137], v[136:137], v[174:175] op_sel_hi:[1,0]
	v_pk_fma_f32 v[146:147], v[164:165], v[146:147], v[176:177]
	v_cvt_f32_f16_sdwa v177, v175 dst_sel:DWORD dst_unused:UNUSED_PAD src0_sel:WORD_1
	v_cvt_f32_f16_e32 v176, v175
	v_pk_mul_f32 v[138:139], v[138:139], v[174:175] op_sel_hi:[1,0]
	v_pk_fma_f32 v[136:137], v[168:169], v[136:137], v[172:173]
	v_cvt_f32_f16_sdwa v173, v170 dst_sel:DWORD dst_unused:UNUSED_PAD src0_sel:WORD_1
	v_cvt_f32_f16_e32 v172, v170
	v_cvt_f32_f16_sdwa v175, v171 dst_sel:DWORD dst_unused:UNUSED_PAD src0_sel:WORD_1
	v_cvt_f32_f16_e32 v174, v171
	ds_read2_b32 v[170:171], v192 offset0:160 offset1:176
	v_pk_fma_f32 v[138:139], v[164:165], v[138:139], v[176:177]
	s_waitcnt lgkmcnt(0)
	v_pk_mul_f32 v[118:119], v[118:119], v[170:171] op_sel_hi:[1,0]
	v_pk_mul_f32 v[116:117], v[116:117], v[170:171] op_sel_hi:[1,0]
	v_pk_fma_f32 v[118:119], v[164:165], v[118:119], v[174:175]
	v_pk_fma_f32 v[116:117], v[168:169], v[116:117], v[172:173]
	v_cvt_f32_f16_sdwa v173, v166 dst_sel:DWORD dst_unused:UNUSED_PAD src0_sel:WORD_1
	v_cvt_f32_f16_e32 v172, v166
	v_cvt_f32_f16_sdwa v175, v167 dst_sel:DWORD dst_unused:UNUSED_PAD src0_sel:WORD_1
	v_cvt_f32_f16_e32 v174, v167
	v_mov_b32_e32 v166, v171
	v_pk_mul_f32 v[114:115], v[114:115], v[166:167] op_sel_hi:[1,0]
	v_pk_mul_f32 v[112:113], v[112:113], v[166:167] op_sel_hi:[1,0]
	v_pk_fma_f32 v[114:115], v[164:165], v[114:115], v[174:175]
	v_pk_fma_f32 v[112:113], v[168:169], v[112:113], v[172:173]
	s_waitcnt vmcnt(2) lgkmcnt(0)
	v_pk_mul_f32 v[166:167], v[198:199], v[202:203]
	v_pk_mul_f32 v[168:169], v[196:197], v[200:201]
	v_pk_mul_f32 v[164:165], s[16:17], v[166:167] op_sel_hi:[0,1]
	v_pk_mul_f32 v[166:167], s[16:17], v[168:169] op_sel_hi:[0,1]
	v_cvt_f32_f16_sdwa v169, v140 dst_sel:DWORD dst_unused:UNUSED_PAD src0_sel:WORD_1
	v_cvt_f32_f16_e32 v168, v140
	v_cvt_f32_f16_sdwa v171, v141 dst_sel:DWORD dst_unused:UNUSED_PAD src0_sel:WORD_1
	v_cvt_f32_f16_e32 v170, v141
	ds_read2_b32 v[140:141], v192 offset1:16
	s_waitcnt lgkmcnt(0)
	v_pk_mul_f32 v[84:85], v[84:85], v[140:141] op_sel_hi:[1,0]
	v_pk_mul_f32 v[86:87], v[86:87], v[140:141] op_sel_hi:[1,0]
	v_pk_fma_f32 v[84:85], v[166:167], v[84:85], v[168:169]
	v_cvt_f32_f16_sdwa v169, v132 dst_sel:DWORD dst_unused:UNUSED_PAD src0_sel:WORD_1
	v_cvt_f32_f16_e32 v168, v132
	v_mov_b32_e32 v132, v141
	v_pk_fma_f32 v[86:87], v[164:165], v[86:87], v[170:171]
	v_cvt_f32_f16_sdwa v171, v133 dst_sel:DWORD dst_unused:UNUSED_PAD src0_sel:WORD_1
	v_cvt_f32_f16_e32 v170, v133
	v_pk_mul_f32 v[78:79], v[78:79], v[132:133] op_sel_hi:[1,0]
	v_pk_mul_f32 v[76:77], v[76:77], v[132:133] op_sel_hi:[1,0]
	v_cvt_f32_f16_sdwa v133, v128 dst_sel:DWORD dst_unused:UNUSED_PAD src0_sel:WORD_1
	v_cvt_f32_f16_e32 v132, v128
	v_cvt_f32_f16_sdwa v141, v129 dst_sel:DWORD dst_unused:UNUSED_PAD src0_sel:WORD_1
	v_cvt_f32_f16_e32 v140, v129
	ds_read2_b32 v[128:129], v192 offset0:32 offset1:48
	v_pk_fma_f32 v[78:79], v[164:165], v[78:79], v[170:171]
	v_pk_fma_f32 v[76:77], v[166:167], v[76:77], v[168:169]
	s_waitcnt lgkmcnt(0)
; __device__ __forceinline__ float f16lo(unsigned w) { return (float)__builtin_bit_cast(f16x2, w)[0]; }
; __device__ __forceinline__ float f16hi(unsigned w) { return (float)__builtin_bit_cast(f16x2, w)[1]; }
;     __device__ __forceinline__ void fused(f32x4 (&acc)[2][2][4][2], const Unit& u, int wr, int wc, int fr, int fq, PG8_LAS unsigned char* lds, int wid, int lane) const {
;     ...
;         for (int bj = 0; bj < 2; ++bj)
; #pragma unroll
;             for (int n = 0; n < 2; ++n) {
;                 const int c = col0 + bj * HALF + n * 4;
;                 const f32x4 gg = *(const f32x4*)(gate + (size_t)b * 9216 + c) * *(const f32x4*)(gpost + c) * res_w;
; #pragma unroll
;                 for (int ai = 0; ai < 2; ++ai)
; #pragma unroll
;                     for (int m = 0; m < 4; ++m) { const int r = ai * HALF + wr * 64 + m * 16 + fr;
;                         const unsigned w0 = n ? pre[ai][m][bj].z : pre[ai][m][bj].x, w1 = n ? pre[ai][m][bj].w : pre[ai][m][bj].y;
;                         const f32x4 xv = {f16lo(w0), f16hi(w0), f16lo(w1), f16hi(w1)};
;                         acc[ai][bj][m][n] = xv + gg * (acc[ai][bj][m][n] * S[r]); }
;                 asm volatile("" ::: "memory");
;             }
	v_pk_mul_f32 v[60:61], v[60:61], v[128:129] op_sel_hi:[1,0]
	v_pk_mul_f32 v[62:63], v[62:63], v[128:129] op_sel_hi:[1,0]
	v_pk_fma_f32 v[60:61], v[166:167], v[60:61], v[132:133]
	v_cvt_f32_f16_sdwa v133, v124 dst_sel:DWORD dst_unused:UNUSED_PAD src0_sel:WORD_1
	v_cvt_f32_f16_e32 v132, v124
	v_mov_b32_e32 v124, v129
	v_pk_fma_f32 v[62:63], v[164:165], v[62:63], v[140:141]
	v_cvt_f32_f16_sdwa v141, v125 dst_sel:DWORD dst_unused:UNUSED_PAD src0_sel:WORD_1
	v_cvt_f32_f16_e32 v140, v125
	v_pk_mul_f32 v[58:59], v[58:59], v[124:125] op_sel_hi:[1,0]
	v_pk_mul_f32 v[56:57], v[56:57], v[124:125] op_sel_hi:[1,0]
	v_cvt_f32_f16_sdwa v125, v120 dst_sel:DWORD dst_unused:UNUSED_PAD src0_sel:WORD_1
	v_cvt_f32_f16_e32 v124, v120
	v_cvt_f32_f16_sdwa v129, v121 dst_sel:DWORD dst_unused:UNUSED_PAD src0_sel:WORD_1
	v_cvt_f32_f16_e32 v128, v121
	ds_read2_b32 v[120:121], v192 offset0:128 offset1:144
	v_pk_fma_f32 v[58:59], v[164:165], v[58:59], v[140:141]
	v_pk_fma_f32 v[56:57], v[166:167], v[56:57], v[132:133]
	s_waitcnt lgkmcnt(0)
	v_pk_mul_f32 v[48:49], v[48:49], v[120:121] op_sel_hi:[1,0]
	v_pk_mul_f32 v[50:51], v[50:51], v[120:121] op_sel_hi:[1,0]
	v_pk_fma_f32 v[48:49], v[166:167], v[48:49], v[124:125]
	v_cvt_f32_f16_sdwa v125, v108 dst_sel:DWORD dst_unused:UNUSED_PAD src0_sel:WORD_1
	v_cvt_f32_f16_e32 v124, v108
	v_mov_b32_e32 v108, v121
	v_pk_fma_f32 v[50:51], v[164:165], v[50:51], v[128:129]
	v_cvt_f32_f16_sdwa v129, v109 dst_sel:DWORD dst_unused:UNUSED_PAD src0_sel:WORD_1
	v_cvt_f32_f16_e32 v128, v109
	v_pk_mul_f32 v[46:47], v[46:47], v[108:109] op_sel_hi:[1,0]
	v_pk_mul_f32 v[44:45], v[44:45], v[108:109] op_sel_hi:[1,0]
	v_cvt_f32_f16_sdwa v109, v104 dst_sel:DWORD dst_unused:UNUSED_PAD src0_sel:WORD_1
	v_cvt_f32_f16_e32 v108, v104
	v_cvt_f32_f16_sdwa v121, v105 dst_sel:DWORD dst_unused:UNUSED_PAD src0_sel:WORD_1
	v_cvt_f32_f16_e32 v120, v105
	ds_read2_b32 v[104:105], v192 offset0:160 offset1:176
	v_pk_fma_f32 v[46:47], v[164:165], v[46:47], v[128:129]
	v_pk_fma_f32 v[44:45], v[166:167], v[44:45], v[124:125]
	s_waitcnt lgkmcnt(0)
	v_pk_mul_f32 v[42:43], v[42:43], v[104:105] op_sel_hi:[1,0]
	v_pk_mul_f32 v[40:41], v[40:41], v[104:105] op_sel_hi:[1,0]
	v_pk_fma_f32 v[42:43], v[164:165], v[42:43], v[120:121]
	v_pk_fma_f32 v[40:41], v[166:167], v[40:41], v[108:109]
	v_cvt_f32_f16_sdwa v109, v100 dst_sel:DWORD dst_unused:UNUSED_PAD src0_sel:WORD_1
	v_cvt_f32_f16_e32 v108, v100
	v_cvt_f32_f16_sdwa v121, v101 dst_sel:DWORD dst_unused:UNUSED_PAD src0_sel:WORD_1
	v_cvt_f32_f16_e32 v120, v101
	v_mov_b32_e32 v100, v105
	v_pk_mul_f32 v[38:39], v[38:39], v[100:101] op_sel_hi:[1,0]
	v_pk_mul_f32 v[36:37], v[36:37], v[100:101] op_sel_hi:[1,0]
	v_pk_fma_f32 v[38:39], v[164:165], v[38:39], v[120:121]
	v_pk_fma_f32 v[36:37], v[166:167], v[36:37], v[108:109]
	ds_read2_b32 v[124:125], v192 offset1:16
	v_cvt_f32_f16_sdwa v109, v142 dst_sel:DWORD dst_unused:UNUSED_PAD src0_sel:WORD_1
	v_cvt_f32_f16_e32 v108, v142
	v_cvt_f32_f16_sdwa v121, v143 dst_sel:DWORD dst_unused:UNUSED_PAD src0_sel:WORD_1
	v_cvt_f32_f16_e32 v120, v143
	s_waitcnt lgkmcnt(0)
	v_pk_mul_f32 v[34:35], v[34:35], v[124:125] op_sel_hi:[1,0]
	v_pk_mul_f32 v[32:33], v[32:33], v[124:125] op_sel_hi:[1,0]
	v_mov_b32_e32 v124, v125
	v_pk_mul_f32 v[30:31], v[30:31], v[124:125] op_sel_hi:[1,0]
	v_pk_mul_f32 v[28:29], v[28:29], v[124:125] op_sel_hi:[1,0]
	ds_read2_b32 v[124:125], v192 offset0:32 offset1:48
	s_waitcnt lgkmcnt(0)
	v_pk_mul_f32 v[26:27], v[26:27], v[124:125] op_sel_hi:[1,0]
	v_pk_mul_f32 v[24:25], v[24:25], v[124:125] op_sel_hi:[1,0]
	v_mov_b32_e32 v124, v125
	v_pk_mul_f32 v[22:23], v[22:23], v[124:125] op_sel_hi:[1,0]
	v_pk_mul_f32 v[20:21], v[20:21], v[124:125] op_sel_hi:[1,0]
	s_waitcnt vmcnt(0)
; __device__ __forceinline__ float f16lo(unsigned w) { return (float)__builtin_bit_cast(f16x2, w)[0]; }
; __device__ __forceinline__ float f16hi(unsigned w) { return (float)__builtin_bit_cast(f16x2, w)[1]; }
; __device__ __forceinline__ void panel_rstd(const f32x4 (&v)[2][2][4][2], const Unit& u, int wr, int wc, int fr, int fq, PG8_LAS unsigned char* lds, int wid, int lane,
;                                            float* xslots, unsigned* cnt, unsigned want, float eps) {
;     ...
; #pragma unroll
;     for (int ai = 0; ai < 2; ++ai)
; #pragma unroll
;         for (int m = 0; m < 4; ++m) {
;             float s = 0.f;
; #pragma unroll
;             for (int bj = 0; bj < 2; ++bj)
; #pragma unroll
;                 for (int n = 0; n < 2; ++n) { const f32x4 x = v[ai][bj][m][n]; s += (x[0] * x[0] + x[1] * x[1]) + (x[2] * x[2] + x[3] * x[3]); }
;             s += __shfl_xor(s, 16); s += __shfl_xor(s, 32);
;             if (fq == 0) P[(ai * HALF + wr * 64 + m * 16 + fr) * 4 + wc] = s;
;     __device__ __forceinline__ void fused(f32x4 (&acc)[2][2][4][2], const Unit& u, int wr, int wc, int fr, int fq, PG8_LAS unsigned char* lds, int wid, int lane) const {
;     ...
;         for (int bj = 0; bj < 2; ++bj)
; #pragma unroll
;             for (int n = 0; n < 2; ++n) {
;                 const int c = col0 + bj * HALF + n * 4;
;                 const f32x4 gg = *(const f32x4*)(gate + (size_t)b * 9216 + c) * *(const f32x4*)(gpost + c) * res_w;
; #pragma unroll
;                 for (int ai = 0; ai < 2; ++ai)
; #pragma unroll
;                     for (int m = 0; m < 4; ++m) { const int r = ai * HALF + wr * 64 + m * 16 + fr;
;                         const unsigned w0 = n ? pre[ai][m][bj].z : pre[ai][m][bj].x, w1 = n ? pre[ai][m][bj].w : pre[ai][m][bj].y;
;                         const f32x4 xv = {f16lo(w0), f16hi(w0), f16lo(w1), f16hi(w1)};
;                         acc[ai][bj][m][n] = xv + gg * (acc[ai][bj][m][n] * S[r]); }
;                 asm volatile("" ::: "memory");
;             }
;         if (HH) panel_rstd(acc, u, wr, wc, fr, fq, lds, wid, lane, xbuf + (size_t)16384 * 4, cnt, want1 + 32u, 1e-6f);
	v_pk_mul_f32 v[100:101], v[216:217], v[238:239]
	v_pk_mul_f32 v[104:105], v[214:215], v[236:237]
	v_pk_mul_f32 v[100:101], s[16:17], v[100:101] op_sel_hi:[0,1]
	v_pk_mul_f32 v[104:105], s[16:17], v[104:105] op_sel_hi:[0,1]
	v_pk_fma_f32 v[34:35], v[100:101], v[34:35], v[120:121]
	v_pk_fma_f32 v[32:33], v[104:105], v[32:33], v[108:109]
	v_cvt_f32_f16_sdwa v109, v134 dst_sel:DWORD dst_unused:UNUSED_PAD src0_sel:WORD_1
	v_cvt_f32_f16_e32 v108, v134
	v_cvt_f32_f16_sdwa v121, v135 dst_sel:DWORD dst_unused:UNUSED_PAD src0_sel:WORD_1
	v_cvt_f32_f16_e32 v120, v135
	v_pk_fma_f32 v[28:29], v[104:105], v[28:29], v[108:109]
	v_cvt_f32_f16_sdwa v109, v130 dst_sel:DWORD dst_unused:UNUSED_PAD src0_sel:WORD_1
	v_pk_fma_f32 v[30:31], v[100:101], v[30:31], v[120:121]
	v_cvt_f32_f16_e32 v108, v130
	v_cvt_f32_f16_sdwa v121, v131 dst_sel:DWORD dst_unused:UNUSED_PAD src0_sel:WORD_1
	v_cvt_f32_f16_e32 v120, v131
	v_pk_fma_f32 v[24:25], v[104:105], v[24:25], v[108:109]
	v_cvt_f32_f16_sdwa v109, v126 dst_sel:DWORD dst_unused:UNUSED_PAD src0_sel:WORD_1
	v_pk_fma_f32 v[26:27], v[100:101], v[26:27], v[120:121]
	v_cvt_f32_f16_e32 v108, v126
	v_cvt_f32_f16_sdwa v121, v127 dst_sel:DWORD dst_unused:UNUSED_PAD src0_sel:WORD_1
	v_cvt_f32_f16_e32 v120, v127
	v_pk_fma_f32 v[20:21], v[104:105], v[20:21], v[108:109]
	v_cvt_f32_f16_sdwa v109, v122 dst_sel:DWORD dst_unused:UNUSED_PAD src0_sel:WORD_1
	v_pk_fma_f32 v[22:23], v[100:101], v[22:23], v[120:121]
	v_cvt_f32_f16_e32 v108, v122
	v_cvt_f32_f16_sdwa v121, v123 dst_sel:DWORD dst_unused:UNUSED_PAD src0_sel:WORD_1
	v_cvt_f32_f16_e32 v120, v123
	ds_read2_b32 v[122:123], v192 offset0:128 offset1:144
	s_waitcnt lgkmcnt(0)
	v_pk_mul_f32 v[16:17], v[16:17], v[122:123] op_sel_hi:[1,0]
	s_nop 0
	v_pk_fma_f32 v[16:17], v[104:105], v[16:17], v[108:109]
	v_cvt_f32_f16_sdwa v109, v110 dst_sel:DWORD dst_unused:UNUSED_PAD src0_sel:WORD_1
	v_cvt_f32_f16_e32 v108, v110
	v_mov_b32_e32 v110, v123
	v_pk_mul_f32 v[18:19], v[18:19], v[122:123] op_sel_hi:[1,0]
	v_pk_mul_f32 v[12:13], v[12:13], v[110:111] op_sel_hi:[1,0]
	v_pk_fma_f32 v[18:19], v[100:101], v[18:19], v[120:121]
	v_cvt_f32_f16_sdwa v121, v111 dst_sel:DWORD dst_unused:UNUSED_PAD src0_sel:WORD_1
	v_cvt_f32_f16_e32 v120, v111
	v_pk_mul_f32 v[14:15], v[14:15], v[110:111] op_sel_hi:[1,0]
	v_pk_fma_f32 v[12:13], v[104:105], v[12:13], v[108:109]
	v_cvt_f32_f16_sdwa v109, v106 dst_sel:DWORD dst_unused:UNUSED_PAD src0_sel:WORD_1
	v_cvt_f32_f16_e32 v108, v106
	v_cvt_f32_f16_sdwa v111, v107 dst_sel:DWORD dst_unused:UNUSED_PAD src0_sel:WORD_1
	v_cvt_f32_f16_e32 v110, v107
	ds_read2_b32 v[106:107], v192 offset0:160 offset1:176
	v_pk_fma_f32 v[14:15], v[100:101], v[14:15], v[120:121]
	s_waitcnt lgkmcnt(0)
	v_pk_mul_f32 v[10:11], v[10:11], v[106:107] op_sel_hi:[1,0]
	v_pk_mul_f32 v[8:9], v[8:9], v[106:107] op_sel_hi:[1,0]
	v_pk_fma_f32 v[10:11], v[100:101], v[10:11], v[110:111]
	v_pk_fma_f32 v[8:9], v[104:105], v[8:9], v[108:109]
	v_cvt_f32_f16_sdwa v109, v102 dst_sel:DWORD dst_unused:UNUSED_PAD src0_sel:WORD_1
	v_cvt_f32_f16_e32 v108, v102
	v_cvt_f32_f16_sdwa v111, v103 dst_sel:DWORD dst_unused:UNUSED_PAD src0_sel:WORD_1
	v_cvt_f32_f16_e32 v110, v103
	v_mov_b32_e32 v102, v107
	v_pk_mul_f32 v[6:7], v[6:7], v[102:103] op_sel_hi:[1,0]
	v_pk_mul_f32 v[4:5], v[4:5], v[102:103] op_sel_hi:[1,0]
	v_pk_fma_f32 v[6:7], v[100:101], v[6:7], v[110:111]
	v_pk_fma_f32 v[4:5], v[104:105], v[4:5], v[108:109]
	s_cbranch_scc1 .LBB0_783
	v_mul_f32_e32 v100, v97, v97
	v_mul_f32_e32 v101, v99, v99
	v_fmac_f32_e32 v100, v96, v96
	v_fmac_f32_e32 v101, v98, v98
	v_add_f32_e32 v100, v100, v101
	v_mul_f32_e32 v101, v161, v161
	v_mul_f32_e32 v102, v163, v163
	v_fmac_f32_e32 v101, v160, v160
	v_fmac_f32_e32 v102, v162, v162
	v_add_f32_e32 v101, v101, v102
	v_add_f32_e32 v100, v100, v101
	v_mul_f32_e32 v101, v85, v85
	v_mul_f32_e32 v102, v87, v87
	v_fmac_f32_e32 v101, v84, v84
	v_fmac_f32_e32 v102, v86, v86
	v_add_f32_e32 v101, v101, v102
	v_add_f32_e32 v100, v100, v101
	v_mul_f32_e32 v101, v33, v33
	v_mul_f32_e32 v102, v35, v35
	v_fmac_f32_e32 v101, v32, v32
	v_fmac_f32_e32 v102, v34, v34
	v_add_f32_e32 v101, v101, v102
	v_add_f32_e32 v100, v100, v101
	v_mov_b32_e32 v101, v100
	s_nop 1
	v_permlane16_swap_b32_e32 v101, v100
	s_waitcnt lgkmcnt(0)
	v_add_f32_e32 v100, v100, v101
	v_mov_b32_e32 v101, v100
	s_nop 1
	v_permlane32_swap_b32_e32 v101, v100
	s_and_saveexec_b64 s[16:17], s[0:1]
	s_cbranch_execz .LBB0_756
	s_lshl_b32 s11, s38, 10
	s_add_i32 s11, s48, s11
	v_lshl_add_u32 v102, v219, 4, s11
	s_waitcnt lgkmcnt(0)
	v_add_f32_e32 v100, v100, v101
	ds_write_b32 v102, v100

;     __device__ __forceinline__ void fused(f32x4 (&acc)[2][2][4][2], const Unit& u, int wr, int wc, int fr, int fq, PG8_LAS unsigned char* lds, int wid, int lane) const {
;     ...
;         for (int bj = 0; bj < 2; ++bj) {
;             const int c = col0 + bj * HALF;
;             f32x4 sh[2], sg[2];
; #pragma unroll
;             for (int n = 0; n < 2; ++n) { sh[n] = (f32x4){0.f, 0.f, 0.f, 0.f}; sg[n] = sh[n];
;                 if (HH) { sh[n] = *(const f32x4*)(shift + (size_t)b * 9216 + c + 4 * n); sg[n] = (*(const f32x4*)(shift + (size_t)b * 9216 + 1024 + c + 4 * n) + 1.0f) * *(const f32x4*)(gpre + c + 4 * n); } }
.LBB0_783:
	s_add_u32 s0, s20, s35
	s_addc_u32 s1, s21, s34
	s_add_u32 s6, s0, 0x1000
	s_addc_u32 s7, s1, 0
	v_cndmask_b32_e64 v2, 0, 1, s[8:9]
	v_lshl_add_u64 v[110:111], s[0:1], 0, v[208:209]
	v_lshl_add_u64 v[120:121], s[6:7], 0, v[208:209]
	v_lshl_add_u64 v[108:109], s[18:19], 0, v[208:209]
	s_waitcnt lgkmcnt(0)
	v_mov_b32_e32 v100, 0
	v_cmp_ne_u32_e64 s[0:1], 1, v2
	s_andn2_b64 vcc, exec, s[8:9]
	v_mov_b32_e32 v104, 0
	v_mov_b32_e32 v105, 0
	v_mov_b32_e32 v106, 0
	v_mov_b32_e32 v107, 0
	v_mov_b32_e32 v142, 0
	v_mov_b32_e32 v143, 0
	v_mov_b32_e32 v164, 0
	v_mov_b32_e32 v165, 0
	s_cbranch_vccnz .LBB0_785
	flat_load_dwordx4 v[104:107], v[110:111]
	flat_load_dwordx4 v[122:125], v[120:121]
	flat_load_dwordx4 v[244:247], v[108:109]
	flat_load_dwordx4 v[196:199], v[110:111] offset:16
	flat_load_dwordx4 v[200:203], v[120:121] offset:16
	flat_load_dwordx4 v[248:251], v[108:109] offset:16
	s_waitcnt vmcnt(3) lgkmcnt(0)
	v_pk_add_f32 v[102:103], v[124:125], 1.0 op_sel_hi:[1,0]
	v_pk_add_f32 v[126:127], v[122:123], 1.0 op_sel_hi:[1,0]
	v_pk_mul_f32 v[164:165], v[102:103], v[246:247]
	v_pk_mul_f32 v[142:143], v[126:127], v[244:245]
.LBB0_785:
	s_and_b64 vcc, exec, s[0:1]
	v_mov_b32_e32 v101, 0
	v_mov_b32_e32 v102, 0
	v_mov_b32_e32 v103, 0
	v_mov_b32_e32 v166, 0
	v_mov_b32_e32 v167, 0
	v_mov_b32_e32 v168, 0
	v_mov_b32_e32 v169, 0
	s_cbranch_vccnz .LBB0_787
	s_waitcnt vmcnt(0) lgkmcnt(0)
	v_mov_b32_e32 v100, v196
	v_mov_b32_e32 v101, v197
	v_mov_b32_e32 v102, v198
	v_mov_b32_e32 v103, v199
	v_pk_add_f32 v[124:125], v[202:203], 1.0 op_sel_hi:[1,0]
	v_pk_add_f32 v[126:127], v[200:201], 1.0 op_sel_hi:[1,0]
	v_pk_mul_f32 v[168:169], v[124:125], v[250:251]
	v_pk_mul_f32 v[166:167], v[126:127], v[248:249]

;     __device__ __forceinline__ void fused(f32x4 (&acc)[2][2][4][2], const Unit& u, int wr, int wc, int fr, int fq, PG8_LAS unsigned char* lds, int wid, int lane) const {
;     ...
;         for (int bj = 0; bj < 2; ++bj) {
;             const int c = col0 + bj * HALF;
;             f32x4 sh[2], sg[2];
; #pragma unroll
;             for (int n = 0; n < 2; ++n) { sh[n] = (f32x4){0.f, 0.f, 0.f, 0.f}; sg[n] = sh[n];
;                 if (HH) { sh[n] = *(const f32x4*)(shift + (size_t)b * 9216 + c + 4 * n); sg[n] = (*(const f32x4*)(shift + (size_t)b * 9216 + 1024 + c + 4 * n) + 1.0f) * *(const f32x4*)(gpre + c + 4 * n); } }
.LBB0_827:
	v_or_b32_e32 v0, 0x80, v0
	v_ashrrev_i32_e32 v1, 31, v0
	v_lshl_add_u64 v[106:107], v[0:1], 2, s[6:7]
	v_mov_b32_e32 v52, 0
	s_and_b64 vcc, exec, s[0:1]
	v_mov_b32_e32 v64, 0
	v_mov_b32_e32 v65, 0
	v_mov_b32_e32 v66, 0
	v_mov_b32_e32 v67, 0
	v_mov_b32_e32 v0, 0
	v_mov_b32_e32 v1, 0
	v_mov_b32_e32 v100, 0
	v_mov_b32_e32 v101, 0
	s_cbranch_vccnz .LBB0_829
	flat_load_dwordx4 v[64:67], v[110:111] offset:512
	flat_load_dwordx4 v[100:103], v[106:107]
	flat_load_dwordx4 v[244:247], v[108:109] offset:512
	flat_load_dwordx4 v[196:199], v[110:111] offset:528
	flat_load_dwordx4 v[200:203], v[106:107] offset:16
	flat_load_dwordx4 v[248:251], v[108:109] offset:528
	s_waitcnt vmcnt(3) lgkmcnt(0)
	v_pk_add_f32 v[0:1], v[102:103], 1.0 op_sel_hi:[1,0]
	v_pk_add_f32 v[54:55], v[100:101], 1.0 op_sel_hi:[1,0]
	v_pk_mul_f32 v[100:101], v[0:1], v[246:247]
	v_pk_mul_f32 v[0:1], v[54:55], v[244:245]
.LBB0_829:
	s_and_b64 vcc, exec, s[0:1]
	v_mov_b32_e32 v53, 0
	v_mov_b32_e32 v54, 0
	v_mov_b32_e32 v55, 0
	v_mov_b32_e32 v102, 0
	v_mov_b32_e32 v103, 0
	v_mov_b32_e32 v104, 0
	v_mov_b32_e32 v105, 0
	s_cbranch_vccnz .LBB0_831
	s_waitcnt vmcnt(0) lgkmcnt(0)
	v_mov_b32_e32 v52, v196
	v_mov_b32_e32 v53, v197
	v_mov_b32_e32 v54, v198
	v_mov_b32_e32 v55, v199
	v_pk_add_f32 v[106:107], v[202:203], 1.0 op_sel_hi:[1,0]
	v_pk_add_f32 v[110:111], v[200:201], 1.0 op_sel_hi:[1,0]
	v_pk_mul_f32 v[104:105], v[106:107], v[250:251]
	v_pk_mul_f32 v[102:103], v[110:111], v[248:249]

; __device__ __forceinline__ unsigned xb_add(unsigned* p, unsigned v) { return __hip_atomic_fetch_add(p, v, __ATOMIC_RELAXED, __HIP_MEMORY_SCOPE_AGENT); }
; __device__ __forceinline__ void xcd_barrier(const XcdBarrier& b) {
;     asm volatile("s_waitcnt vmcnt(0)" ::: "memory");
;     __syncthreads();
;     if (threadIdx.x == 0) {
;         unsigned* bar = b.bar;
;         __builtin_amdgcn_s_waitcnt(0);
;         unsigned nloc = b.st[0], nx = b.st[1];
;         if (nloc == 0u) { xcd_barrier_complete(bar, b.x, nloc, nx); b.st[0] = nloc; b.st[1] = nx; }
;         const unsigned old = xb_add(&bar[XB_XSUB(b.x)], 1u);
.LBB0_890:
	v_mov_b64_e32 v[196:197], 0
	v_mov_b64_e32 v[198:199], 0
	v_mov_b64_e32 v[200:201], 0x580
	v_mov_b64_e32 v[202:203], 0x57f
	v_readlane_b32 s0, v254, 63
	v_readlane_b32 s4, v255, 39
	v_readlane_b32 s1, v255, 0
	v_readlane_b32 s5, v255, 40
	s_and_b64 s[0:1], s[0:1], s[4:5]
	s_and_b64 vcc, exec, s[0:1]
	s_cbranch_vccnz .LBB0_247
	s_getreg_b32 s4, hwreg(HW_REG_XCC_ID, 0, 4)
	s_waitcnt vmcnt(0)
	s_waitcnt vmcnt(0) lgkmcnt(0)
	s_barrier
	s_mov_b64 s[0:1], exec
	v_readlane_b32 s6, v252, 32
	v_readlane_b32 s7, v252, 33
	s_and_b64 s[6:7], s[0:1], s[6:7]
	s_mov_b64 exec, s[6:7]
	s_cbranch_execz .LBB0_246
	v_readlane_b32 s5, v254, 24
	s_waitcnt vmcnt(0) expcnt(0) lgkmcnt(0)
	s_and_b32 s10, s4, 15
	v_mov_b32_e32 v0, s5
	ds_read_b32 v2, v0
	v_readlane_b32 s5, v254, 25
	s_waitcnt lgkmcnt(0)
	v_cmp_ne_u32_e32 vcc, 0, v2
	v_mov_b32_e32 v0, s5
	ds_read_b32 v0, v0
	s_cbranch_vccnz .LBB0_907
	s_mov_b32 s11, 1
	s_branch .LBB0_895
